# w_out conversion (layers>0) moved from H-start (all WGs) to A-start on WGs 128-255 which have slack in phase A
# baseline (speedup 1.0000x reference)
.LBB0_265:
	s_or_b64 exec, exec, s[4:5]
	v_readlane_b32 s0, v252, 47
	v_readlane_b32 s1, v252, 48
	s_andn2_b64 vcc, exec, s[0:1]
	s_cbranch_vccnz .LBB0_368
	s_cmp_lt_u32 s2, 0x80
	s_cbranch_scc1 .LBB0_368
	s_bfe_i64 s[0:1], s[52:53], 0x200000
	v_readlane_b32 s72, v252, 61
	s_lshl_b64 s[0:1], s[0:1], 13
	v_readlane_b32 s82, v253, 7
	v_readlane_b32 s83, v253, 8
	s_add_u32 s0, s82, s0
	s_addc_u32 s1, s83, s1
	s_mov_b64 s[6:7], s[38:39]
	v_readlane_b32 s36, v254, 50
	s_add_u32 s4, s0, 0xffffe000
	v_readlane_b32 s44, v254, 58
	v_readlane_b32 s80, v253, 5
	s_addc_u32 s5, s1, -1
	s_lshl_b64 s[0:1], s[52:53], 26
	s_lshl_b64 s[12:13], s[52:53], 13
	s_lshl_b64 s[18:19], s[52:53], 24
	s_lshl_b32 s16, s52, 4
	s_lshl_b64 s[20:21], s[52:53], 22
	v_readlane_b32 s38, v254, 52
	v_readlane_b32 s39, v254, 53
	s_lshl_b32 s44, s52, 9
	v_readlane_b32 s81, v253, 6
	s_mov_b64 s[38:39], s[6:7]
	s_add_u32 s6, s80, s0
	v_readlane_b32 s78, v253, 3
	s_addc_u32 s7, s81, s1
	v_readlane_b32 s79, v253, 4
	s_add_u32 s8, s78, s0
	v_readlane_b32 s74, v252, 63
	v_readlane_b32 s40, v254, 54
	s_addc_u32 s9, s79, s1
	v_readlane_b32 s75, v253, 0
	v_readlane_b32 s37, v254, 51
	v_readlane_b32 s41, v254, 55
	s_add_u32 s40, s74, s12
	v_readlane_b32 s42, v254, 56
	s_addc_u32 s41, s75, s13
	s_mov_b32 s1, s37
	v_readlane_b32 s73, v252, 62
	v_readlane_b32 s76, v253, 1
	v_readlane_b32 s77, v253, 2
	v_readlane_b32 s43, v254, 57
	v_readlane_b32 s45, v254, 59
	v_readlane_b32 s46, v254, 60
	v_readlane_b32 s47, v254, 61
	v_readlane_b32 s48, v254, 62
	v_readlane_b32 s49, v254, 63
	s_add_u32 s42, s72, s18
	v_writelane_b32 v254, s0, 50
	s_addc_u32 s43, s73, s19
	v_readlane_b32 s68, v252, 6
	v_writelane_b32 v254, s1, 51
	v_readlane_b32 s84, v253, 9
	v_readlane_b32 s85, v253, 10
	v_readlane_b32 s86, v253, 11
	v_readlane_b32 s87, v253, 12
	v_readlane_b32 s72, v252, 10
	v_readlane_b32 s73, v252, 11
	v_readlane_b32 s74, v252, 12
	v_readlane_b32 s75, v252, 13
	v_readlane_b32 s76, v252, 14
	v_readlane_b32 s77, v252, 15
	v_readlane_b32 s78, v252, 16
	v_readlane_b32 s79, v252, 17
	v_readlane_b32 s80, v252, 18
	v_readlane_b32 s81, v252, 19
	v_readlane_b32 s82, v252, 20
	v_readlane_b32 s83, v252, 21
	v_writelane_b32 v254, s2, 52
	v_writelane_b32 v254, s3, 53
	v_readlane_b32 s72, v252, 22
	v_writelane_b32 v254, s4, 54
	v_readlane_b32 s73, v252, 23
	v_readlane_b32 s74, v252, 24
	v_readlane_b32 s75, v252, 25
	v_readlane_b32 s76, v252, 26
	v_readlane_b32 s77, v252, 27
	v_readlane_b32 s78, v252, 28
	v_readlane_b32 s79, v252, 29
	v_readlane_b32 s80, v252, 30
	v_readlane_b32 s81, v252, 31
	v_readlane_b32 s82, v252, 32
	v_readlane_b32 s83, v252, 33
	v_readlane_b32 s50, v255, 0
	v_readlane_b32 s51, v255, 1
	s_mov_b32 s45, s37
	v_readlane_b32 s69, v252, 7
	s_add_u32 s46, s68, s20
	v_writelane_b32 v254, s5, 55
	v_writelane_b32 v255, s14, 0
	v_readlane_b32 s84, v252, 34
	v_readlane_b32 s85, v252, 35
	v_readlane_b32 s86, v252, 36
	v_readlane_b32 s87, v252, 37
	s_mov_b64 s[72:73], s[76:77]
	s_addc_u32 s47, s69, s21
	v_writelane_b32 v254, s6, 56
	v_writelane_b32 v255, s15, 1
	s_lshl_b64 s[0:1], s[44:45], 2
	s_mov_b64 s[74:75], s[78:79]
	s_mov_b64 s[76:77], s[80:81]
	s_mov_b64 s[78:79], s[82:83]
	s_mov_b64 s[80:81], s[84:85]
	v_writelane_b32 v254, s7, 57
	s_add_u32 s48, s80, s0
	s_mul_i32 s22, s52, 0x300000
	v_writelane_b32 v254, s8, 58
	s_mov_b64 s[82:83], s[86:87]
	s_addc_u32 s49, s81, s1
	s_mul_hi_u32 s17, s52, 0x300000
	v_writelane_b32 v254, s9, 59
	s_add_u32 s50, s82, s22
	v_writelane_b32 v254, s10, 60
	s_addc_u32 s51, s83, s17
	v_writelane_b32 v254, s11, 61
	s_add_u32 s58, s78, s0
	v_readlane_b32 s70, v252, 8
	v_writelane_b32 v254, s12, 62
	s_addc_u32 s59, s79, s1
	s_mul_i32 s1, s52, 0x1880000
	v_readlane_b32 s71, v252, 9
	v_writelane_b32 v254, s13, 63
	s_mul_hi_u32 s0, s52, 0x1880000
	s_add_u32 s70, s76, s1
	s_addc_u32 s71, s77, s0
	s_movk_i32 s17, 0x4000
	s_movk_i32 s18, 0x100
	v_readlane_b32 s19, v254, 38
	v_readlane_b32 s20, v254, 36
	v_readlane_b32 s21, v254, 32
	v_readlane_b32 s22, v252, 46
	s_nop 3
	s_addk_i32 s19, 0xf500
	s_addk_i32 s20, 0xd400
	s_add_i32 s21, s21, 0xfffd4000
	s_addk_i32 s22, 0xfa80
	s_branch .LBB0_269

.LBB0_269:
	s_cmpk_lt_u32 s22, 0x330
	s_cbranch_scc1 .Lmy_cvt_go
	s_cmpk_lt_u32 s22, 0x730
	s_cbranch_scc1 .LBB0_268

.LBB0_963:
	s_or_b64 exec, exec, s[6:7]
	s_and_b64 vcc, exec, s[4:5]
	s_waitcnt lgkmcnt(0)
	s_barrier
	s_branch .LBB0_1045
	v_readlane_b32 s0, v253, 44
	v_readlane_b32 s1, v253, 45
	s_andn2_b64 vcc, exec, s[0:1]
	s_cbranch_vccnz .LBB0_1045
	v_readlane_b32 s72, v252, 61
	v_readlane_b32 s12, v254, 50
	v_readlane_b32 s82, v253, 7
	v_readlane_b32 s0, v255, 25
	v_readlane_b32 s13, v254, 51
	v_readlane_b32 s83, v253, 8
	v_readlane_b32 s1, v255, 26
	s_add_u32 s8, s82, s0
	s_mov_b32 s97, s13
	s_addc_u32 s9, s83, s1
	v_readlane_b32 s22, v254, 60
	s_lshl_b64 s[0:1], s[96:97], 24
	s_lshl_b32 s12, s96, 4
	s_lshl_b64 s[6:7], s[96:97], 22
	s_lshl_b32 s40, s96, 9
	v_readlane_b32 s73, v252, 62
	v_readlane_b32 s74, v252, 63
	v_readlane_b32 s75, v253, 0
	v_readlane_b32 s76, v253, 1
	v_readlane_b32 s77, v253, 2
	v_readlane_b32 s78, v253, 3
	v_readlane_b32 s79, v253, 4
	v_readlane_b32 s80, v253, 5
	v_readlane_b32 s81, v253, 6
	v_readlane_b32 s23, v254, 61
	s_add_u32 s22, s72, s0
	v_readlane_b32 s14, v254, 52
	v_readlane_b32 s15, v254, 53
	v_readlane_b32 s24, v254, 62
	s_mov_b32 s41, s13
	s_addc_u32 s23, s73, s1
	v_readlane_b32 s68, v252, 6
	v_readlane_b32 s25, v254, 63
	s_mul_hi_u32 s13, s96, 0x300000
	s_mul_i32 s14, s96, 0x300000
	s_mul_hi_u32 s15, s96, 0x1880000
	v_readlane_b32 s69, v252, 7
	s_add_u32 s24, s68, s6
	s_mov_b32 s1, s41
	v_readlane_b32 s16, v254, 54
	v_readlane_b32 s17, v254, 55
	v_readlane_b32 s18, v254, 56
	v_readlane_b32 s19, v254, 57
	v_readlane_b32 s20, v254, 58
	v_readlane_b32 s21, v254, 59
	s_addc_u32 s25, s69, s7
	v_writelane_b32 v254, s0, 50
	v_readlane_b32 s84, v253, 9
	v_readlane_b32 s85, v253, 10
	v_writelane_b32 v254, s1, 51
	v_writelane_b32 v254, s2, 52
	v_writelane_b32 v254, s3, 53
	v_readlane_b32 s86, v253, 11
	v_readlane_b32 s87, v253, 12
	v_readlane_b32 s72, v252, 10
	v_readlane_b32 s73, v252, 11
	v_readlane_b32 s74, v252, 12
	v_readlane_b32 s75, v252, 13
	v_readlane_b32 s76, v252, 14
	v_readlane_b32 s77, v252, 15
	v_readlane_b32 s78, v252, 16
	v_readlane_b32 s79, v252, 17
	v_readlane_b32 s80, v252, 18
	v_readlane_b32 s81, v252, 19
	v_readlane_b32 s82, v252, 20
	v_readlane_b32 s83, v252, 21
	v_writelane_b32 v254, s4, 54
	v_readlane_b32 s26, v255, 0
	v_readlane_b32 s27, v255, 1
	v_writelane_b32 v254, s5, 55
	v_writelane_b32 v255, s14, 0
	v_readlane_b32 s72, v252, 22
	v_writelane_b32 v254, s6, 56
	v_writelane_b32 v255, s15, 1
	s_lshl_b64 s[0:1], s[40:41], 2
	v_readlane_b32 s84, v252, 34
	v_writelane_b32 v254, s7, 57
	v_readlane_b32 s73, v252, 23
	v_readlane_b32 s85, v252, 35
	s_add_u32 s72, s84, s0
	v_writelane_b32 v254, s8, 58
	v_readlane_b32 s74, v252, 24
	v_readlane_b32 s86, v252, 36
	s_addc_u32 s73, s85, s1
	v_writelane_b32 v254, s9, 59
	v_readlane_b32 s75, v252, 25
	v_readlane_b32 s87, v252, 37
	s_add_u32 s74, s86, s14
	v_writelane_b32 v254, s10, 60
	v_readlane_b32 s76, v252, 26
	v_readlane_b32 s82, v252, 32
	s_addc_u32 s75, s87, s13
	v_writelane_b32 v254, s11, 61
	v_readlane_b32 s77, v252, 27
	v_readlane_b32 s83, v252, 33
	s_add_u32 s76, s82, s0
	s_mul_i32 s16, s96, 0x1880000
	v_writelane_b32 v254, s12, 62
	v_readlane_b32 s78, v252, 28
	v_readlane_b32 s80, v252, 30
	s_addc_u32 s77, s83, s1
	v_writelane_b32 v254, s13, 63
	v_readlane_b32 s79, v252, 29
	v_readlane_b32 s81, v252, 31
	s_add_u32 s78, s80, s16
	s_addc_u32 s79, s81, s15
	s_lshl_b32 s13, s30, 7
	v_readlane_b32 s14, v254, 41
	v_readlane_b32 s15, v254, 34
	v_readlane_b32 s16, v253, 43
	v_readlane_b32 s70, v252, 8
	v_readlane_b32 s71, v252, 9
	s_branch .LBB0_968
